# v16 + SGU: W fragments loaded once at item start into spare VGPRs, MFMA loop rotates registers instead of load+wait per k-step
# baseline (speedup 1.0000x reference)
; __device__ __forceinline__ void sgu_phase(LAS unsigned char* lds, const bf16_t* U, const bf16_t* GV, const bf16_t* SZ, const float* stats, const float* vg, const float* vb,
;                                           const bf16_t* wsb, const float* b_s, bf16_t* Y, int G, int bid) {
;     ...
;     for (int itl = bid; itl < 1024; itl += G) {
;         const int it = xmap ? ((bid & 7) * 128 + (bid >> 3) + 32 * (itl >> 8)) : itl;
;         const int ci = it >> 4, g = it & 15, row0 = ci * 128;
;         __syncthreads();
;         if (tid < 128) {
;             const float* sp = stats + (size_t)(row0 + tid) * 64; float s = 0.f, ss = 0.f;
; #pragma unroll
;             for (int i = 0; i < 16; ++i) { const f32x4 q = *(const f32x4*)(sp + i * 4); s += q[0] + q[2]; ss += q[1] + q[3]; }
;             const float mean = s * (1.0f / DM), var = ss * (1.0f / DM) - mean * mean;
;             rstat[tid] = (f32x2){mean, rsqrtf(var + 1e-5f)};
;         }
;         __syncthreads();
; #pragma unroll
;         for (int i = 0; i < 4; ++i) {
;             const int id = tid + 512 * i, r = id >> 4, cc = id & 15;
;             const u32x4 w = *(const u32x4*)(GV + (size_t)(row0 + r) * DM + g * 128 + cc * 8);
;             const f32x2 st = rstat[r];
;             const f32x4 g0 = *(const f32x4*)(vg + g * 128 + cc * 8), g1 = *(const f32x4*)(vg + g * 128 + cc * 8 + 4);
;             const f32x4 b0 = *(const f32x4*)(vb + g * 128 + cc * 8), b1 = *(const f32x4*)(vb + g * 128 + cc * 8 + 4);
;             float f[8] = {bf_lo(w.x), bf_hi(w.x), bf_lo(w.y), bf_hi(w.y), bf_lo(w.z), bf_hi(w.z), bf_lo(w.w), bf_hi(w.w)};
; #pragma unroll
;             for (int j = 0; j < 8; ++j) {
;                 const float gg = j < 4 ? g0[j & 3] : g1[j & 3], bb = j < 4 ? b0[j & 3] : b1[j & 3];
;                 const float vn = (f[j] - st.x) * st.y * gg + bb;
;                 *(LAS bf16_t*)(vnT + (cc * 8 + j) * VST + (((r >> 3) ^ cc) << 4) + (r & 7) * 2) = (bf16_t)(cvt_pk_bf16(vn, 0.f) & 0xffffu);
;             }
;         }
;         __syncthreads();
;         f32x4 acc[8];
; #pragma unroll
;         for (int ct = 0; ct < 8; ++ct) acc[ct] = (f32x4){0.f, 0.f, 0.f, 0.f};
;         const bf16_t* wrow = wsb + ((size_t)g * 128 + wid * 16 + fr) * 128 + fq * 8;
;         const int nks = (wid >> 1) + 1;
;         for (int ks = 0; ks < nks; ++ks) {
;             const bf16x8 wf = *(const bf16x8*)(wrow + ks * 32);
.LBB0_235:
	s_lshr_b32 s0, s26, 8
	s_and_b32 s1, s0, 1
	s_lshr_b32 s0, s0, 1
	s_lshl_b32 s0, s0, 4
	s_add_i32 s0, s0, s1
	s_add_i32 s18, s3, s0
	s_lshl_b32 s0, s18, 3
	s_and_b32 s27, s0, 0xffffff80
	s_waitcnt lgkmcnt(0)
	s_barrier
	s_lshl_b32 s24, s18, 7
	s_and_b32 s36, s24, 0x780
	s_mov_b32 s25, 0
	v_add_lshl_u32 v158, v47, s36, 8
	v_mov_b32_e32 v159, 0
	v_lshl_add_u64 v[158:159], v[42:43], 0, v[158:159]
	global_load_dwordx4 v[102:105], v[158:159], off
	global_load_dwordx4 v[106:109], v[158:159], off offset:64
	global_load_dwordx4 v[150:153], v[158:159], off offset:128
	global_load_dwordx4 v[154:157], v[158:159], off offset:192
	v_add_u32_e32 v240, s27, v47
	v_ashrrev_i32_e32 v241, 31, v240
	v_lshlrev_b64 v[240:241], 11, v[240:241]
	v_or3_b32 v240, v240, v40, s36
	v_lshlrev_b64 v[240:241], 1, v[240:241]
	v_lshl_add_u64 v[240:241], s[8:9], 0, v[240:241]
	v_add_lshl_u32 v242, s36, v47, 2
	global_load_dword v126, v242, s[28:29]
	global_load_dwordx2 v[110:111], v[240:241], off
	global_load_dwordx2 v[112:113], v[240:241], off offset:32
	global_load_dwordx2 v[114:115], v[240:241], off offset:64
	global_load_dwordx2 v[116:117], v[240:241], off offset:96
	global_load_dwordx2 v[118:119], v[240:241], off offset:128
	global_load_dwordx2 v[120:121], v[240:241], off offset:160
	global_load_dwordx2 v[122:123], v[240:241], off offset:192
	global_load_dwordx2 v[124:125], v[240:241], off offset:224
	s_lshl_b32 s24, s36, 1
	v_lshl_add_u64 v[236:237], v[34:35], 0, s[24:25]
	s_lshl_b32 s24, s36, 2
	v_lshl_add_u64 v[244:245], v[38:39], 0, s[24:25]
	v_lshl_add_u64 v[246:247], v[36:37], 0, s[24:25]
	v_or_b32_e32 v238, s27, v214
	v_ashrrev_i32_e32 v239, 31, v238
	v_lshlrev_b64 v[238:239], 12, v[238:239]
	v_lshl_add_u64 v[238:239], v[236:237], 0, v[238:239]
	global_load_dwordx4 v[130:133], v[238:239], off
	global_load_dwordx4 v[134:137], v[244:245], off
	global_load_dwordx4 v[138:141], v[246:247], off
	global_load_dwordx4 v[142:145], v[246:247], off offset:16
	global_load_dwordx4 v[146:149], v[244:245], off offset:16
	v_or_b32_e32 v238, s27, v50
	v_ashrrev_i32_e32 v239, 31, v238
	v_lshlrev_b64 v[238:239], 12, v[238:239]
	v_lshl_add_u64 v[238:239], v[236:237], 0, v[238:239]
	global_load_dwordx4 v[170:173], v[238:239], off
	global_load_dwordx4 v[174:177], v[244:245], off
	global_load_dwordx4 v[178:181], v[246:247], off
	global_load_dwordx4 v[182:185], v[246:247], off offset:16
	global_load_dwordx4 v[186:189], v[244:245], off offset:16
	v_or_b32_e32 v238, s27, v52
	v_ashrrev_i32_e32 v239, 31, v238
	v_lshlrev_b64 v[238:239], 12, v[238:239]
	v_lshl_add_u64 v[238:239], v[236:237], 0, v[238:239]
	global_load_dwordx4 v[190:193], v[238:239], off
	global_load_dwordx4 v[194:197], v[244:245], off
	global_load_dwordx4 v[198:201], v[246:247], off
	global_load_dwordx4 v[202:205], v[246:247], off offset:16
	global_load_dwordx4 v[206:209], v[244:245], off offset:16
	v_add_u32_e32 v238, s27, v54
	v_ashrrev_i32_e32 v239, 31, v238
	v_lshlrev_b64 v[238:239], 12, v[238:239]
	v_lshl_add_u64 v[238:239], v[236:237], 0, v[238:239]
	global_load_dwordx4 v[216:219], v[238:239], off
	global_load_dwordx4 v[220:223], v[244:245], off
	global_load_dwordx4 v[224:227], v[246:247], off
	global_load_dwordx4 v[228:231], v[246:247], off offset:16
	global_load_dwordx4 v[232:235], v[244:245], off offset:16
	s_and_saveexec_b64 s[24:25], vcc
	s_bitcmp1_b32 s26, 8
	s_cbranch_scc1 .LBB0_237
	s_cbranch_execz .LBB0_237
	v_or_b32_e32 v0, s27, v164
	v_ashrrev_i32_e32 v1, 31, v0
	v_lshlrev_b64 v[0:1], 8, v[0:1]
	v_lshl_add_u64 v[44:45], s[16:17], 0, v[0:1]
	global_load_dwordx4 v[0:3], v[44:45], off
	global_load_dwordx4 v[4:7], v[44:45], off offset:16
	global_load_dwordx4 v[8:11], v[44:45], off offset:32
	global_load_dwordx4 v[12:15], v[44:45], off offset:48
	global_load_dwordx4 v[16:19], v[44:45], off offset:64
	global_load_dwordx4 v[20:23], v[44:45], off offset:80
	global_load_dwordx4 v[24:27], v[44:45], off offset:96
	global_load_dwordx4 v[28:31], v[44:45], off offset:112
	global_load_dwordx4 v[70:73], v[44:45], off offset:128
	global_load_dwordx4 v[74:77], v[44:45], off offset:144
	global_load_dwordx4 v[78:81], v[44:45], off offset:160
	global_load_dwordx4 v[82:85], v[44:45], off offset:176
	global_load_dwordx4 v[86:89], v[44:45], off offset:192
	global_load_dwordx4 v[90:93], v[44:45], off offset:208
	global_load_dwordx4 v[94:97], v[44:45], off offset:224
	global_load_dwordx4 v[98:101], v[44:45], off offset:240
	s_waitcnt vmcnt(15)
	v_pk_add_f32 v[0:1], v[0:1], v[2:3]
	s_waitcnt vmcnt(14)
	v_pk_add_f32 v[2:3], v[4:5], v[6:7]
	v_pk_add_f32 v[0:1], v[0:1], 0 op_sel_hi:[1,0]
	s_waitcnt vmcnt(13)
	v_pk_add_f32 v[4:5], v[8:9], v[10:11]
	v_pk_add_f32 v[0:1], v[0:1], v[2:3]
	s_waitcnt vmcnt(12)
	v_pk_add_f32 v[6:7], v[12:13], v[14:15]
	v_pk_add_f32 v[0:1], v[0:1], v[4:5]
	s_waitcnt vmcnt(11)
	v_pk_add_f32 v[8:9], v[16:17], v[18:19]
	v_pk_add_f32 v[0:1], v[0:1], v[6:7]
	s_waitcnt vmcnt(10)
	v_pk_add_f32 v[10:11], v[20:21], v[22:23]
	v_pk_add_f32 v[0:1], v[0:1], v[8:9]
	s_waitcnt vmcnt(9)
	v_pk_add_f32 v[12:13], v[24:25], v[26:27]
	v_pk_add_f32 v[0:1], v[0:1], v[10:11]
	s_waitcnt vmcnt(8)
	v_pk_add_f32 v[14:15], v[28:29], v[30:31]
	v_pk_add_f32 v[0:1], v[0:1], v[12:13]
	s_waitcnt vmcnt(7)
	v_pk_add_f32 v[16:17], v[70:71], v[72:73]
	v_pk_add_f32 v[0:1], v[0:1], v[14:15]
	s_waitcnt vmcnt(6)
	v_pk_add_f32 v[18:19], v[74:75], v[76:77]
	v_pk_add_f32 v[0:1], v[0:1], v[16:17]
	s_waitcnt vmcnt(5)
	v_pk_add_f32 v[20:21], v[78:79], v[80:81]
	v_pk_add_f32 v[0:1], v[0:1], v[18:19]
	s_waitcnt vmcnt(4)
	v_pk_add_f32 v[22:23], v[82:83], v[84:85]
	v_pk_add_f32 v[0:1], v[0:1], v[20:21]
	s_waitcnt vmcnt(3)
	v_pk_add_f32 v[24:25], v[86:87], v[88:89]
	v_pk_add_f32 v[0:1], v[0:1], v[22:23]
	s_waitcnt vmcnt(2)
	v_pk_add_f32 v[26:27], v[90:91], v[92:93]
	v_pk_add_f32 v[0:1], v[0:1], v[24:25]
	s_waitcnt vmcnt(1)
	v_pk_add_f32 v[28:29], v[94:95], v[96:97]
	v_pk_add_f32 v[0:1], v[0:1], v[26:27]
	s_waitcnt vmcnt(0)
	v_pk_add_f32 v[30:31], v[98:99], v[100:101]
	v_pk_add_f32 v[0:1], v[0:1], v[28:29]
	s_nop 0
	v_pk_add_f32 v[0:1], v[0:1], v[30:31]
	s_nop 0
	v_pk_mul_f32 v[0:1], v[0:1], s[22:23] op_sel_hi:[1,0]
	s_nop 0
	v_fma_f32 v1, -v0, v0, v1
	v_add_f32_e32 v1, 0x3727c5ac, v1
	v_mul_f32_e32 v2, 0x4b800000, v1
	v_cmp_gt_f32_e64 s[0:1], s23, v1
	s_nop 1
	v_cndmask_b32_e64 v1, v1, v2, s[0:1]
	v_rsq_f32_e32 v1, v1
	s_nop 0
	v_mul_f32_e32 v2, 0x45800000, v1
	v_cndmask_b32_e64 v1, v1, v2, s[0:1]
	ds_write_b64 v46, v[0:1] offset:34816

; #define LAS __attribute__((address_space(3)))
; __device__ __forceinline__ unsigned cvt_pk_bf16(float lo, float hi) { unsigned r; asm volatile("v_cvt_pk_bf16_f32 %0, %1, %2" : "=v"(r) : "v"(lo), "v"(hi)); return r; }
; __device__ __forceinline__ float bf_lo(unsigned w) { return __uint_as_float(w << 16); }
; __device__ __forceinline__ float bf_hi(unsigned w) { return __uint_as_float(w & 0xffff0000u); }
; __device__ __forceinline__ void sgu_phase(LAS unsigned char* lds, const bf16_t* U, const bf16_t* GV, const bf16_t* SZ, const float* stats, const float* vg, const float* vb,
;                                           const bf16_t* wsb, const float* b_s, bf16_t* Y, int G, int bid) {
;     ...
;         const bf16_t* wrow = wsb + ((size_t)g * 128 + wid * 16 + fr) * 128 + fq * 8;
;         const int nks = (wid >> 1) + 1;
;         for (int ks = 0; ks < nks; ++ks) {
;             const bf16x8 wf = *(const bf16x8*)(wrow + ks * 32);
; #pragma unroll
;             for (int ct = 0; ct < 8; ++ct) {
;                 const bf16x8 vf = *(const LAS bf16x8*)(vnT + (ct * 16 + fr) * VST + (((ks * 4 + fq) ^ (ct * 2 + (fr >> 3))) << 4));
;                 acc[ct] = __builtin_amdgcn_mfma_f32_16x16x32_bf16(vf, wf, acc[ct], 0, 0, 0);
;             }
;         }
;         const int t = wid * 16 + fr; const float bs = b_s[g * 128 + t];
;         const size_t ro = (size_t)(row0 + t) * DM + g * 128 + 4 * fq;
; #pragma unroll
;         for (int ct = 0; ct < 8; ++ct) {
;             const u32x2 uw = *(const u32x2*)(U + ro + ct * 16);
;             const float y0 = bf_lo(uw.x) * (acc[ct][0] + bs), y1 = bf_hi(uw.x) * (acc[ct][1] + bs);
;             const float y2 = bf_lo(uw.y) * (acc[ct][2] + bs), y3 = bf_hi(uw.y) * (acc[ct][3] + bs);
;             u32x2 o; o.x = cvt_pk_bf16(y0, y1); o.y = cvt_pk_bf16(y2, y3);
;             *(u32x2*)(Y + ro + ct * 16) = o;
;         }
.LBB0_238:
	v_mov_b32_e32 v72, v102
	v_mov_b32_e32 v73, v103
	v_mov_b32_e32 v74, v104
	v_mov_b32_e32 v75, v105
	v_xor_b32_e32 v32, v69, v48
	v_xor_b32_e32 v71, v69, v57
	v_xor_b32_e32 v76, v69, v58
	v_xor_b32_e32 v77, v69, v59
	v_xor_b32_e32 v78, v69, v60
	v_xor_b32_e32 v79, v69, v61
	v_xor_b32_e32 v80, v69, v62
	v_xor_b32_e32 v81, v69, v63
	v_lshl_add_u32 v32, v32, 4, v56
	v_lshl_add_u32 v71, v71, 4, v56
	v_lshl_add_u32 v84, v76, 4, v56
	v_lshl_add_u32 v85, v77, 4, v56
	v_lshl_add_u32 v86, v78, 4, v56
	v_lshl_add_u32 v87, v79, 4, v56
	v_lshl_add_u32 v88, v80, 4, v56
	v_lshl_add_u32 v89, v81, 4, v56
	ds_read_b128 v[76:79], v32
	ds_read_b128 v[80:83], v71 offset:4352
	v_add_u32_e32 v70, -1, v70
	v_cmp_eq_u32_e64 s[0:1], 0, v70
	v_add_u32_e32 v69, 4, v69
	s_or_b64 s[24:25], s[0:1], s[24:25]
	v_lshl_add_u64 v[44:45], v[44:45], 0, 64
	s_waitcnt vmcnt(0) lgkmcnt(1)
	v_mfma_f32_16x16x32_bf16 v[28:31], v[76:79], v[72:75], v[28:31]
	ds_read_b128 v[76:79], v84 offset:8704
	s_waitcnt lgkmcnt(1)
	v_mfma_f32_16x16x32_bf16 v[24:27], v[80:83], v[72:75], v[24:27]
	ds_read_b128 v[80:83], v85 offset:13056
	s_waitcnt lgkmcnt(1)
	v_mfma_f32_16x16x32_bf16 v[20:23], v[76:79], v[72:75], v[20:23]
	ds_read_b128 v[76:79], v86 offset:17408
	s_waitcnt lgkmcnt(1)
	v_mfma_f32_16x16x32_bf16 v[16:19], v[80:83], v[72:75], v[16:19]
	ds_read_b128 v[80:83], v87 offset:21760
	s_waitcnt lgkmcnt(1)
	v_mfma_f32_16x16x32_bf16 v[12:15], v[76:79], v[72:75], v[12:15]
	ds_read_b128 v[76:79], v88 offset:26112
	s_waitcnt lgkmcnt(1)
	v_mfma_f32_16x16x32_bf16 v[8:11], v[80:83], v[72:75], v[8:11]
	ds_read_b128 v[80:83], v89 offset:30464
	s_waitcnt lgkmcnt(1)
	v_mfma_f32_16x16x32_bf16 v[4:7], v[76:79], v[72:75], v[4:7]
	s_waitcnt lgkmcnt(0)
	v_mfma_f32_16x16x32_bf16 v[0:3], v[80:83], v[72:75], v[0:3]
	v_mov_b32_e32 v102, v106
	v_mov_b32_e32 v103, v107
	v_mov_b32_e32 v104, v108
	v_mov_b32_e32 v105, v109
	v_mov_b32_e32 v106, v150
	v_mov_b32_e32 v107, v151
	v_mov_b32_e32 v108, v152
	v_mov_b32_e32 v109, v153
	v_mov_b32_e32 v150, v154
	v_mov_b32_e32 v151, v155
	v_mov_b32_e32 v152, v156
	v_mov_b32_e32 v153, v157
	s_andn2_b64 exec, exec, s[24:25]
	s_cbranch_execnz .LBB0_238
	s_or_b64 exec, exec, s[24:25]
	v_add_u32_e32 v44, s27, v47
	v_ashrrev_i32_e32 v45, 31, v44
	v_lshlrev_b64 v[44:45], 11, v[44:45]
	v_or3_b32 v45, v45, 0, 0
	v_or3_b32 v44, v44, v40, s36
	v_lshlrev_b64 v[44:45], 1, v[44:45]
	v_add_lshl_u32 v32, s36, v47, 2
	v_lshl_add_u64 v[70:71], s[8:9], 0, v[44:45]
	v_lshl_add_u64 v[44:45], s[38:39], 0, v[44:45]
	v_mov_b32_e32 v72, v110
	v_mov_b32_e32 v73, v111
	s_add_i32 s26, s26, s34
	s_cmpk_gt_i32 s26, 0x3ff
	v_add_f32_e32 v28, v28, v126
	v_add_f32_e32 v29, v29, v126
	v_lshlrev_b32_e32 v69, 16, v72
	v_and_b32_e32 v72, 0xffff0000, v72
	v_add_f32_e32 v30, v30, v126
	v_add_f32_e32 v31, v31, v126
	v_lshlrev_b32_e32 v74, 16, v73
	v_and_b32_e32 v73, 0xffff0000, v73
	v_mul_f32_e32 v28, v28, v69
	v_mul_f32_e32 v29, v29, v72
	v_mul_f32_e32 v30, v30, v74
	v_mul_f32_e32 v31, v31, v73
	v_cvt_pk_bf16_f32 v28, v28, v29
	v_cvt_pk_bf16_f32 v29, v30, v31
	global_store_dwordx2 v[44:45], v[28:29], off
	v_mov_b32_e32 v28, v112
	v_mov_b32_e32 v29, v113
	v_add_f32_e32 v24, v24, v126
	v_add_f32_e32 v25, v25, v126
	v_add_f32_e32 v26, v26, v126
	v_add_f32_e32 v27, v27, v126
	v_add_f32_e32 v20, v20, v126
	v_add_f32_e32 v21, v21, v126
	v_add_f32_e32 v22, v22, v126
	v_add_f32_e32 v23, v23, v126
	v_add_f32_e32 v16, v16, v126
	v_add_f32_e32 v17, v17, v126
	v_add_f32_e32 v18, v18, v126
	v_add_f32_e32 v19, v19, v126
	v_add_f32_e32 v12, v12, v126
	v_add_f32_e32 v13, v13, v126
	v_add_f32_e32 v14, v14, v126
	v_add_f32_e32 v15, v15, v126
	v_add_f32_e32 v8, v8, v126
	v_add_f32_e32 v9, v9, v126
	v_add_f32_e32 v10, v10, v126
	v_add_f32_e32 v11, v11, v126
	v_add_f32_e32 v4, v4, v126
	v_add_f32_e32 v5, v5, v126
	v_add_f32_e32 v6, v6, v126
	v_add_f32_e32 v7, v7, v126
	v_add_f32_e32 v0, v0, v126
	v_add_f32_e32 v1, v1, v126
	v_add_f32_e32 v2, v2, v126
	v_add_f32_e32 v3, v3, v126
	v_lshlrev_b32_e32 v30, 16, v28
	v_and_b32_e32 v28, 0xffff0000, v28
	v_lshlrev_b32_e32 v31, 16, v29
	v_and_b32_e32 v29, 0xffff0000, v29
	v_mul_f32_e32 v24, v24, v30
	v_mul_f32_e32 v25, v25, v28
	v_mul_f32_e32 v26, v26, v31
	v_mul_f32_e32 v27, v27, v29
	v_cvt_pk_bf16_f32 v24, v24, v25
	v_cvt_pk_bf16_f32 v25, v26, v27
	global_store_dwordx2 v[44:45], v[24:25], off offset:32
	v_mov_b32_e32 v24, v114
	v_mov_b32_e32 v25, v115
	v_lshlrev_b32_e32 v26, 16, v24
	v_and_b32_e32 v24, 0xffff0000, v24
	v_lshlrev_b32_e32 v27, 16, v25
	v_and_b32_e32 v25, 0xffff0000, v25
	v_mul_f32_e32 v20, v20, v26
	v_mul_f32_e32 v21, v21, v24
	v_mul_f32_e32 v22, v22, v27
	v_mul_f32_e32 v23, v23, v25
	v_cvt_pk_bf16_f32 v20, v20, v21
	v_cvt_pk_bf16_f32 v21, v22, v23
	global_store_dwordx2 v[44:45], v[20:21], off offset:64
	v_mov_b32_e32 v20, v116
	v_mov_b32_e32 v21, v117
	v_lshlrev_b32_e32 v22, 16, v20
	v_and_b32_e32 v20, 0xffff0000, v20
	v_lshlrev_b32_e32 v23, 16, v21
	v_and_b32_e32 v21, 0xffff0000, v21
	v_mul_f32_e32 v16, v16, v22
	v_mul_f32_e32 v17, v17, v20
	v_mul_f32_e32 v18, v18, v23
	v_mul_f32_e32 v19, v19, v21
	v_cvt_pk_bf16_f32 v16, v16, v17
	v_cvt_pk_bf16_f32 v17, v18, v19
	global_store_dwordx2 v[44:45], v[16:17], off offset:96
	v_mov_b32_e32 v16, v118
	v_mov_b32_e32 v17, v119
	v_lshlrev_b32_e32 v18, 16, v16
	v_and_b32_e32 v16, 0xffff0000, v16
	v_lshlrev_b32_e32 v19, 16, v17
	v_and_b32_e32 v17, 0xffff0000, v17
	v_mul_f32_e32 v12, v12, v18
	v_mul_f32_e32 v13, v13, v16
	v_mul_f32_e32 v14, v14, v19
	v_mul_f32_e32 v15, v15, v17
	v_cvt_pk_bf16_f32 v12, v12, v13
	v_cvt_pk_bf16_f32 v13, v14, v15
	global_store_dwordx2 v[44:45], v[12:13], off offset:128
	v_mov_b32_e32 v12, v120
	v_mov_b32_e32 v13, v121
	v_lshlrev_b32_e32 v14, 16, v12
	v_and_b32_e32 v12, 0xffff0000, v12
	v_lshlrev_b32_e32 v15, 16, v13
	v_and_b32_e32 v13, 0xffff0000, v13
	v_mul_f32_e32 v8, v8, v14
	v_mul_f32_e32 v9, v9, v12
	v_mul_f32_e32 v10, v10, v15
	v_mul_f32_e32 v11, v11, v13
	v_cvt_pk_bf16_f32 v8, v8, v9
	v_cvt_pk_bf16_f32 v9, v10, v11
	global_store_dwordx2 v[44:45], v[8:9], off offset:160
	v_mov_b32_e32 v8, v122
	v_mov_b32_e32 v9, v123
	v_lshlrev_b32_e32 v10, 16, v8
	v_and_b32_e32 v8, 0xffff0000, v8
	v_lshlrev_b32_e32 v11, 16, v9
	v_and_b32_e32 v9, 0xffff0000, v9
	v_mul_f32_e32 v4, v4, v10
	v_mul_f32_e32 v5, v5, v8
	v_mul_f32_e32 v6, v6, v11
	v_mul_f32_e32 v7, v7, v9
	v_cvt_pk_bf16_f32 v4, v4, v5
	v_cvt_pk_bf16_f32 v5, v6, v7
	global_store_dwordx2 v[44:45], v[4:5], off offset:192
	v_mov_b32_e32 v4, v124
	v_mov_b32_e32 v5, v125
	v_lshlrev_b32_e32 v6, 16, v4
	v_and_b32_e32 v4, 0xffff0000, v4
	v_lshlrev_b32_e32 v7, 16, v5
	v_and_b32_e32 v5, 0xffff0000, v5
	v_mul_f32_e32 v0, v0, v6
	v_mul_f32_e32 v1, v1, v4
	v_mul_f32_e32 v2, v2, v7
	v_mul_f32_e32 v3, v3, v5
	v_cvt_pk_bf16_f32 v0, v0, v1
	v_cvt_pk_bf16_f32 v1, v2, v3
	global_store_dwordx2 v[44:45], v[0:1], off offset:224
	s_cbranch_scc0 .LBB0_235
